# combine phase rows assigned per XCD; the seam combine -> out-proj (odd layers) is XCD-local too
# baseline (speedup 1.0000x reference)
.Lhw_bar_scope:
	v_readlane_b32 s2, v246, 26
	s_and_b32 s9, s88, 1
	s_lshl_b32 s9, s9, 8
	s_or_b32 s8, s9, 0xe1e
	s_lshr_b32 s8, s8, s2
	v_readlane_b32 s6, v246, 41
	s_and_b32 s8, s8, 1
	s_and_b32 s8, s8, s6
	v_writelane_b32 v246, s8, 42
	s_waitcnt vmcnt(0)
	s_barrier
	v_mov_b32 v0, v194
	s_nop 0
	v_cmp_eq_u32_e32 vcc, 0, v0
	s_and_saveexec_b64 s[0:1], vcc
	s_cbranch_execz .LBB0_108
	s_waitcnt vmcnt(0) expcnt(0) lgkmcnt(0)
	ds_read_b32 v3, v1
	ds_read_b32 v0, v1 offset:4
	s_waitcnt lgkmcnt(1)
	v_cmp_ne_u32_e32 vcc, 0, v3
	s_cbranch_vccnz .LBB0_71
	s_mov_b32 s2, 1
	s_branch .LBB0_54

.LBB0_155:
	s_andn2_b64 vcc, exec, s[10:11]
	s_cbranch_vccnz .LBB0_418
	v_readlane_b32 s2, v246, 25
	s_cmp_lt_i32 s2, 7
	s_mov_b64 s[10:11], -1
	s_cbranch_scc1 .LBB0_259
	v_readlane_b32 s2, v246, 25
	s_cmp_gt_i32 s2, 7
	s_cbranch_scc0 .LBB0_162
	s_mov_b64 s[12:13], s[84:85]
	v_mov_b32 v0, v194
	v_readlane_b32 s2, v246, 16
	s_lshl_b32 s6, s83, 2
	s_lshl_b32 s2, s2, 7
	s_add_i32 s2, s2, s6
	s_waitcnt vmcnt(0) lgkmcnt(0)
	v_ashrrev_i32_e32 v2, 6, v0
	v_add_u32_e32 v2, s2, v2
	s_movk_i32 s2, 0x3000
	v_cmp_gt_i32_e32 vcc, s2, v2
	s_and_saveexec_b64 s[10:11], vcc
	s_movk_i32 s42, 0x100
	v_readlane_b32 s2, v246, 16
	s_lshl_b32 s2, s2, 7
	s_add_i32 s2, s2, 0x5ff
	s_mov_b32 s6, 0x800000
	v_readlane_b32 s43, v247, 54
	s_cbranch_execz .LBB0_161
	s_load_dwordx2 s[18:19], s[12:13], 0x108
	s_load_dwordx2 s[20:21], s[12:13], 0xd8
	s_load_dwordx2 s[28:29], s[12:13], 0xe8
	v_and_b32_e32 v0, 63, v0
	v_lshlrev_b32_e32 v3, 3, v0
	s_waitcnt lgkmcnt(0)
	s_add_u32 s12, s18, 0x3000000
	s_addc_u32 s13, s19, 0
	s_add_u32 s14, s18, 0x4800000
	s_addc_u32 s15, s19, 0
	s_add_u32 s16, s18, 0x19158100
	s_addc_u32 s17, s19, 0
	s_lshl_b64 s[40:41], s[0:1], 9
	s_add_u32 s28, s28, s40
	s_addc_u32 s29, s29, s41
	s_add_u32 s20, s20, s40
	s_addc_u32 s21, s21, s41
	global_load_dwordx2 v[4:5], v3, s[28:29]
	global_load_dwordx2 v[6:7], v3, s[20:21]
	v_and_b32_e32 v10, 64, v200
	v_xor_b32_e32 v3, 32, v200
	v_add_u32_e32 v10, 64, v10
	v_cmp_lt_i32_e32 vcc, v3, v10
	v_lshlrev_b32_e32 v8, 2, v0
	v_mov_b32_e32 v9, v1
	v_cndmask_b32_e32 v3, v200, v3, vcc
	v_lshlrev_b32_e32 v14, 2, v3
	v_xor_b32_e32 v3, 16, v200
	v_cmp_lt_i32_e32 vcc, v3, v10
	v_lshl_add_u64 v[8:9], s[18:19], 0, v[8:9]
	s_mov_b64 s[18:19], 0x14958100
	v_cndmask_b32_e32 v3, v200, v3, vcc
	v_lshlrev_b32_e32 v15, 2, v3
	v_xor_b32_e32 v3, 8, v200
	v_cmp_lt_i32_e32 vcc, v3, v10
	v_lshl_add_u64 v[8:9], v[8:9], 0, s[18:19]
	s_mov_b64 s[40:41], 0
	v_cndmask_b32_e32 v3, v200, v3, vcc
	v_lshlrev_b32_e32 v16, 2, v3
	v_xor_b32_e32 v3, 4, v200
	v_cmp_lt_i32_e32 vcc, v3, v10
	s_nop 1
	v_cndmask_b32_e32 v3, v200, v3, vcc
	v_lshlrev_b32_e32 v17, 2, v3
	v_xor_b32_e32 v3, 2, v200
	v_cmp_lt_i32_e32 vcc, v3, v10
	s_nop 1
	v_cndmask_b32_e32 v3, v200, v3, vcc
	v_lshlrev_b32_e32 v18, 2, v3
	v_xor_b32_e32 v3, 1, v200
	v_cmp_lt_i32_e32 vcc, v3, v10
	s_nop 1
	v_cndmask_b32_e32 v3, v200, v3, vcc
	v_lshlrev_b32_e32 v19, 2, v3
